# v18 plus attention-step trim (dead m0 save/restore, satisfied waits) and SGPR-base LDS-DMA addressing for 8 of 16 K-loop DMAs
# baseline (speedup 1.0000x reference)
.LBB0_482:
	s_lshl_b32 s22, s56, 1
	s_add_i32 s63, s26, s27
	v_add_u32_e32 v0, s22, v242
	s_add_i32 s22, s63, -5
	v_cvt_f32_i32_e32 v99, s22
	ds_read_b64_tr_b16 v[204:205], v0 offset:24576
	ds_read_b64_tr_b16 v[206:207], v0 offset:25088
	v_lshrrev_b32_e32 v99, 16, v99
	v_cndmask_b32_e64 v99, 0, v99, s[8:9]
	v_mov_b32_e32 v100, v240
	v_lshlrev_b32_e32 v101, 16, v99
	v_or_b32_e32 v142, v101, v99
	v_lshl_or_b32 v140, v100, 16, v100
	v_or_b32_e32 v141, v100, v101
	v_add_f32_e32 v99, v82, v83
	v_add_f32_e32 v99, v84, v99
	v_mfma_f32_32x32x16_bf16 v[116:131], v[140:143], v[136:139], 0
	v_add_f32_e32 v99, v85, v99
	v_add_f32_e32 v99, v86, v99
	v_add_f32_e32 v99, v87, v99
	v_cvt_pk_bf16_f32 v168, v82, v83
	v_cvt_pk_bf16_f32 v169, v84, v85
	v_mfma_f32_32x32x16_bf16 v[116:131], v[200:203], v[160:163], v[116:131]
	ds_read_b64_tr_b16 v[82:83], v0 offset:28672
	ds_read_b64_tr_b16 v[84:85], v0 offset:29184
	v_mov_b32_e32 v100, v239
	v_add_f32_e32 v99, v88, v99
	v_lshl_or_b32 v140, v100, 16, v100
	v_or_b32_e32 v141, v100, v101
	v_add_f32_e32 v99, v89, v99
	v_add_f32_e32 v99, v90, v99
	v_mfma_f32_32x32x16_bf16 v[100:115], v[140:143], v[136:139], 0
	v_add_f32_e32 v99, v91, v99
	v_cvt_pk_bf16_f32 v170, v86, v87
	v_cvt_pk_bf16_f32 v171, v88, v89
	v_mfma_f32_32x32x16_bf16 v[100:115], v[196:199], v[160:163], v[100:115]
	ds_read_b64_tr_b16 v[86:87], v0 offset:32768
	ds_read_b64_tr_b16 v[88:89], v0 offset:33280
	v_mfma_f32_32x32x16_bf16 v[116:131], v[192:195], v[152:155], v[116:131]
	v_add_f32_e32 v99, v92, v99
	v_add_f32_e32 v99, v93, v99
	v_add_f32_e32 v99, v94, v99
	v_add_f32_e32 v99, v95, v99
	v_cvt_pk_bf16_f32 v164, v90, v91
	v_cvt_pk_bf16_f32 v165, v92, v93
	ds_read_b64_tr_b16 v[90:91], v0 offset:36864
	ds_read_b64_tr_b16 v[92:93], v0 offset:37376
	v_mfma_f32_32x32x16_bf16 v[100:115], v[188:191], v[152:155], v[100:115]
	v_add_f32_e32 v99, v96, v99
	v_add_f32_e32 v99, v97, v99
	v_add_f32_e32 v99, v66, v99
	v_add_f32_e32 v99, v67, v99
	v_cvt_pk_bf16_f32 v166, v94, v95
	v_cvt_pk_bf16_f32 v167, v96, v97
	ds_read_b64_tr_b16 v[94:95], v0 offset:25600
	ds_read_b64_tr_b16 v[96:97], v0 offset:26112
	v_mfma_f32_32x32x16_bf16 v[116:131], v[184:187], v[148:151], v[116:131]
	v_add_f32_e32 v99, v68, v99
	v_add_f32_e32 v99, v69, v99
	v_add_f32_e32 v99, v70, v99
	v_add_f32_e32 v99, v71, v99
	v_cvt_pk_bf16_f32 v156, v66, v67
	v_cvt_pk_bf16_f32 v157, v68, v69
	ds_read_b64_tr_b16 v[66:67], v0 offset:29696
	ds_read_b64_tr_b16 v[68:69], v0 offset:30208
	v_mfma_f32_32x32x16_bf16 v[100:115], v[180:183], v[148:151], v[100:115]
	v_add_f32_e32 v99, v72, v99
	v_add_f32_e32 v99, v73, v99
	v_add_f32_e32 v99, v74, v99
	v_add_f32_e32 v99, v75, v99
	v_cvt_pk_bf16_f32 v158, v70, v71
	v_cvt_pk_bf16_f32 v159, v72, v73
	ds_read_b64_tr_b16 v[70:71], v0 offset:33792
	ds_read_b64_tr_b16 v[72:73], v0 offset:34304
	v_mfma_f32_32x32x16_bf16 v[116:131], v[176:179], v[132:135], v[116:131]
	v_add_f32_e32 v99, v76, v99
	v_add_f32_e32 v99, v77, v99
	v_add_f32_e32 v99, v78, v99
	v_add_f32_e32 v99, v79, v99
	v_cvt_pk_bf16_f32 v144, v74, v75
	v_cvt_pk_bf16_f32 v145, v76, v77
	ds_read_b64_tr_b16 v[74:75], v0 offset:37888
	ds_read_b64_tr_b16 v[76:77], v0 offset:38400
	v_mfma_f32_32x32x16_bf16 v[100:115], v[172:175], v[132:135], v[100:115]
	v_add_f32_e32 v99, v80, v99
	v_add_f32_e32 v99, v81, v99
	v_add_f32_e32 v99, 0, v99
	v_cvt_pk_bf16_f32 v146, v78, v79
	v_cvt_pk_bf16_f32 v147, v80, v81
	v_lshl_add_u64 v[208:209], v[216:217], 0, s[12:13]
	v_lshl_add_u64 v[78:79], v[208:209], 0, s[48:49]
	s_add_i32 s22, s62, s92
	v_lshl_add_u64 v[210:211], v[218:219], 0, s[12:13]
	s_mov_b32 m0, s22
	s_nop 0
	global_load_lds_dwordx4 v[78:79], off
	v_lshl_add_u64 v[78:79], v[210:211], 0, s[42:43]
	s_lshl_b32 s22, s61, 1
	v_lshl_add_u64 v[222:223], v[220:221], 0, s[12:13]
	s_add_i32 s23, s22, s93
	s_mov_b32 m0, s23
	s_nop 0
	global_load_lds_dwordx4 v[78:79], off
	v_lshl_add_u64 v[78:79], v[222:223], 0, s[42:43]
	s_add_i32 s22, s22, s94
	s_mov_b32 m0, s22
	s_nop 0
	global_load_lds_dwordx4 v[78:79], off
	s_waitcnt lgkmcnt(14)
	v_mfma_f32_32x32x16_bf16 v[50:65], v[168:171], v[204:207], v[50:65]
	ds_read_b64_tr_b16 v[78:79], v0 offset:26624
	ds_read_b64_tr_b16 v[80:81], v0 offset:27136
	v_max_f32_e32 v253, v117, v117
	v_max_f32_e32 v254, v116, v116
	v_max_f32_e32 v253, v254, v253
	v_max3_f32 v254, v118, v119, v101
	v_max3_f32 v253, v253, v100, v102
	s_waitcnt lgkmcnt(14)
	v_mfma_f32_32x32x16_bf16 v[34:49], v[168:171], v[82:85], v[34:49]
	ds_read_b64_tr_b16 v[82:83], v0 offset:30720
	ds_read_b64_tr_b16 v[84:85], v0 offset:31232
	v_max3_f32 v253, v253, v103, v120
	v_max3_f32 v254, v254, v122, v123
	v_max3_f32 v253, v253, v121, v104
	v_max3_f32 v254, v254, v106, v107
	v_max3_f32 v253, v253, v105, v124
	s_waitcnt lgkmcnt(14)
	v_mfma_f32_32x32x16_bf16 v[18:33], v[168:171], v[86:89], v[18:33]
	ds_read_b64_tr_b16 v[86:87], v0 offset:34816
	ds_read_b64_tr_b16 v[88:89], v0 offset:35328
	v_max3_f32 v254, v254, v126, v127
	v_max3_f32 v253, v253, v125, v108
	v_max3_f32 v254, v254, v110, v111
	v_max3_f32 v253, v253, v109, v128
	v_max3_f32 v254, v254, v130, v131
	s_waitcnt lgkmcnt(14)
	v_mfma_f32_32x32x16_bf16 v[2:17], v[168:171], v[90:93], v[2:17]
	ds_read_b64_tr_b16 v[90:91], v0 offset:38912
	ds_read_b64_tr_b16 v[92:93], v0 offset:39424
	v_max3_f32 v253, v253, v129, v112
	v_max3_f32 v254, v254, v114, v115
	v_max3_f32 v253, v253, v113, v254
	v_mov_b32_e32 v254, v253
	s_nop 1
	v_permlane32_swap_b32_e32 v253, v254
	v_max_f32_e32 v254, v254, v254
	v_max_f32_e32 v253, v253, v253
	v_max_f32_e32 v253, v253, v254
	v_cmp_lt_f32_e32 vcc, s88, v253
	s_cmp_lg_u64 vcc, 0
	v_add_f32_e32 v98, v98, v99
	s_cselect_b64 s[56:57], -1, 0
	s_cbranch_vccnz .LBB0_490

.LBB0_485:
	s_add_i32 s22, s61, 0x2000
	s_cmpk_lg_i32 s61, 0x4000
	s_cselect_b32 s96, s22, 0
	s_lshl_b32 s22, s62, 1
	s_add_i32 s63, s63, -4
	v_add_u32_e32 v99, s22, v242
	v_cvt_f32_i32_e32 v70, s63
	ds_read_b64_tr_b16 v[200:201], v99 offset:24576
	ds_read_b64_tr_b16 v[202:203], v99 offset:25088
	v_lshrrev_b32_e32 v70, 16, v70
	v_cndmask_b32_e64 v70, 0, v70, s[8:9]
	v_mov_b32_e32 v71, v240
	v_lshlrev_b32_e32 v72, 16, v70
	v_or_b32_e32 v142, v72, v70
	v_lshl_or_b32 v140, v71, 16, v71
	v_or_b32_e32 v141, v71, v72
	v_add_f32_e32 v70, v116, v117
	v_cvt_pk_bf16_f32 v168, v116, v117
	v_mfma_f32_32x32x16_bf16 v[82:97], v[140:143], v[136:139], 0
	v_cvt_pk_bf16_f32 v169, v118, v119
	v_mfma_f32_32x32x16_bf16 v[82:97], v[66:69], v[160:163], v[82:97]
	v_add_f32_e32 v66, v118, v70
	v_add_f32_e32 v66, v119, v66
	v_add_f32_e32 v66, v120, v66
	v_add_f32_e32 v144, v121, v66
	ds_read_b64_tr_b16 v[116:117], v99 offset:28672
	ds_read_b64_tr_b16 v[118:119], v99 offset:29184
	v_mov_b32_e32 v66, v239
	v_cvt_pk_bf16_f32 v170, v120, v121
	v_lshl_or_b32 v140, v66, 16, v66
	v_or_b32_e32 v141, v66, v72
	v_cvt_pk_bf16_f32 v171, v122, v123
	s_nop 0
	v_mfma_f32_32x32x16_bf16 v[66:81], v[140:143], v[136:139], 0
	v_add_f32_e32 v140, v122, v144
	v_add_f32_e32 v140, v123, v140
	v_add_f32_e32 v140, v124, v140
	v_add_f32_e32 v140, v125, v140
	v_mfma_f32_32x32x16_bf16 v[66:81], v[196:199], v[160:163], v[66:81]
	ds_read_b64_tr_b16 v[120:121], v99 offset:32768
	ds_read_b64_tr_b16 v[122:123], v99 offset:33280
	v_mfma_f32_32x32x16_bf16 v[82:97], v[192:195], v[152:155], v[82:97]
	v_add_f32_e32 v140, v126, v140
	v_add_f32_e32 v140, v127, v140
	v_add_f32_e32 v140, v128, v140
	v_add_f32_e32 v140, v129, v140
	v_cvt_pk_bf16_f32 v164, v124, v125
	v_cvt_pk_bf16_f32 v165, v126, v127
	ds_read_b64_tr_b16 v[124:125], v99 offset:36864
	ds_read_b64_tr_b16 v[126:127], v99 offset:37376
	v_mfma_f32_32x32x16_bf16 v[66:81], v[188:191], v[152:155], v[66:81]
	v_add_f32_e32 v140, v130, v140
	v_add_f32_e32 v140, v131, v140
	v_add_f32_e32 v140, v100, v140
	v_add_f32_e32 v140, v101, v140
	v_cvt_pk_bf16_f32 v166, v128, v129
	v_cvt_pk_bf16_f32 v167, v130, v131
	ds_read_b64_tr_b16 v[128:129], v99 offset:25600
	ds_read_b64_tr_b16 v[130:131], v99 offset:26112
	v_mfma_f32_32x32x16_bf16 v[82:97], v[184:187], v[148:151], v[82:97]
	v_add_f32_e32 v140, v102, v140
	v_add_f32_e32 v140, v103, v140
	v_add_f32_e32 v140, v104, v140
	v_add_f32_e32 v140, v105, v140
	v_cvt_pk_bf16_f32 v156, v100, v101
	v_cvt_pk_bf16_f32 v157, v102, v103
	ds_read_b64_tr_b16 v[100:101], v99 offset:29696
	ds_read_b64_tr_b16 v[102:103], v99 offset:30208
	v_mfma_f32_32x32x16_bf16 v[66:81], v[180:183], v[148:151], v[66:81]
	v_add_f32_e32 v140, v106, v140
	v_add_f32_e32 v140, v107, v140
	v_add_f32_e32 v140, v108, v140
	v_add_f32_e32 v140, v109, v140
	v_cvt_pk_bf16_f32 v158, v104, v105
	v_cvt_pk_bf16_f32 v159, v106, v107
	ds_read_b64_tr_b16 v[104:105], v99 offset:33792
	ds_read_b64_tr_b16 v[106:107], v99 offset:34304
	v_mfma_f32_32x32x16_bf16 v[82:97], v[176:179], v[132:135], v[82:97]
	v_add_f32_e32 v140, v110, v140
	v_add_f32_e32 v140, v111, v140
	v_add_f32_e32 v140, v112, v140
	v_add_f32_e32 v140, v113, v140
	v_cvt_pk_bf16_f32 v144, v108, v109
	v_cvt_pk_bf16_f32 v145, v110, v111
	ds_read_b64_tr_b16 v[108:109], v99 offset:37888
	ds_read_b64_tr_b16 v[110:111], v99 offset:38400
	v_mfma_f32_32x32x16_bf16 v[66:81], v[172:175], v[132:135], v[66:81]
	v_add_f32_e32 v140, v114, v140
	v_add_f32_e32 v140, v115, v140
	v_add_f32_e32 v140, 0, v140
	v_cvt_pk_bf16_f32 v146, v112, v113
	v_cvt_pk_bf16_f32 v147, v114, v115
	v_lshl_add_u64 v[112:113], v[208:209], 0, s[50:51]
	s_add_i32 s22, s61, s92
	s_mov_b32 m0, s22
	s_nop 0
	global_load_lds_dwordx4 v[112:113], off
	v_lshl_add_u64 v[112:113], v[210:211], 0, s[44:45]
	s_lshl_b32 s22, s96, 1
	s_add_i32 s23, s22, s93
	s_mov_b32 m0, s23
	s_nop 0
	global_load_lds_dwordx4 v[112:113], off
	v_lshl_add_u64 v[112:113], v[222:223], 0, s[44:45]
	s_add_i32 s22, s22, s94
	s_mov_b32 m0, s22
	s_nop 0
	global_load_lds_dwordx4 v[112:113], off
	s_waitcnt lgkmcnt(14)
	v_mfma_f32_32x32x16_bf16 v[50:65], v[168:171], v[200:203], v[50:65]
	ds_read_b64_tr_b16 v[112:113], v99 offset:26624
	ds_read_b64_tr_b16 v[114:115], v99 offset:27136
	v_max_f32_e32 v253, v83, v83
	v_max_f32_e32 v254, v82, v82
	v_max_f32_e32 v253, v254, v253
	v_max3_f32 v254, v84, v85, v67
	v_max3_f32 v253, v253, v66, v68
	s_waitcnt lgkmcnt(14)
	v_mfma_f32_32x32x16_bf16 v[34:49], v[168:171], v[116:119], v[34:49]
	ds_read_b64_tr_b16 v[116:117], v99 offset:30720
	ds_read_b64_tr_b16 v[118:119], v99 offset:31232
	v_max3_f32 v253, v253, v69, v86
	v_max3_f32 v254, v254, v88, v89
	v_max3_f32 v253, v253, v87, v70
	v_max3_f32 v254, v254, v72, v73
	v_max3_f32 v253, v253, v71, v90
	s_waitcnt lgkmcnt(14)
	v_mfma_f32_32x32x16_bf16 v[18:33], v[168:171], v[120:123], v[18:33]
	ds_read_b64_tr_b16 v[120:121], v99 offset:34816
	ds_read_b64_tr_b16 v[122:123], v99 offset:35328
	v_max3_f32 v254, v254, v92, v93
	v_max3_f32 v253, v253, v91, v74
	v_max3_f32 v254, v254, v76, v77
	v_max3_f32 v253, v253, v75, v94
	v_max3_f32 v254, v254, v96, v97
	s_waitcnt lgkmcnt(14)
	v_mfma_f32_32x32x16_bf16 v[2:17], v[168:171], v[124:127], v[2:17]
	ds_read_b64_tr_b16 v[124:125], v99 offset:38912
	ds_read_b64_tr_b16 v[126:127], v99 offset:39424
	v_max3_f32 v253, v253, v95, v78
	v_max3_f32 v254, v254, v80, v81
	v_max3_f32 v253, v253, v79, v254
	v_mov_b32_e32 v254, v253
	s_nop 1
	v_permlane32_swap_b32_e32 v253, v254
	v_max_f32_e32 v254, v254, v254
	v_max_f32_e32 v253, v253, v253
	v_max_f32_e32 v253, v253, v254
	v_cmp_lt_f32_e32 vcc, s88, v253
	s_cmp_lg_u64 vcc, 0
	v_add_f32_e32 v98, v98, v140
	s_cselect_b64 s[56:57], -1, 0
	s_cbranch_vccnz .LBB0_493

.LBB0_1352:
	s_lshl_b32 s56, s56, 1
	s_add_i32 s63, s26, s27
	v_add_u32_e32 v0, s56, v242
	s_add_i32 s56, s63, -5
	v_cvt_f32_i32_e32 v99, s56
	ds_read_b64_tr_b16 v[204:205], v0 offset:24576
	ds_read_b64_tr_b16 v[206:207], v0 offset:25088
	v_lshrrev_b32_e32 v99, 16, v99
	v_cndmask_b32_e64 v99, 0, v99, s[10:11]
	v_mov_b32_e32 v100, v240
	v_lshlrev_b32_e32 v101, 16, v99
	v_or_b32_e32 v142, v101, v99
	v_lshl_or_b32 v140, v100, 16, v100
	v_or_b32_e32 v141, v100, v101
	v_add_f32_e32 v99, v82, v83
	v_add_f32_e32 v99, v84, v99
	v_mfma_f32_32x32x16_bf16 v[116:131], v[140:143], v[136:139], 0
	v_add_f32_e32 v99, v85, v99
	v_add_f32_e32 v99, v86, v99
	v_add_f32_e32 v99, v87, v99
	v_cvt_pk_bf16_f32 v168, v82, v83
	v_cvt_pk_bf16_f32 v169, v84, v85
	v_mfma_f32_32x32x16_bf16 v[116:131], v[200:203], v[160:163], v[116:131]
	ds_read_b64_tr_b16 v[82:83], v0 offset:28672
	ds_read_b64_tr_b16 v[84:85], v0 offset:29184
	v_mov_b32_e32 v100, v239
	v_add_f32_e32 v99, v88, v99
	v_lshl_or_b32 v140, v100, 16, v100
	v_or_b32_e32 v141, v100, v101
	v_add_f32_e32 v99, v89, v99
	v_add_f32_e32 v99, v90, v99
	v_mfma_f32_32x32x16_bf16 v[100:115], v[140:143], v[136:139], 0
	v_add_f32_e32 v99, v91, v99
	v_cvt_pk_bf16_f32 v170, v86, v87
	v_cvt_pk_bf16_f32 v171, v88, v89
	v_mfma_f32_32x32x16_bf16 v[100:115], v[196:199], v[160:163], v[100:115]
	ds_read_b64_tr_b16 v[86:87], v0 offset:32768
	ds_read_b64_tr_b16 v[88:89], v0 offset:33280
	v_mfma_f32_32x32x16_bf16 v[116:131], v[192:195], v[152:155], v[116:131]
	v_add_f32_e32 v99, v92, v99
	v_add_f32_e32 v99, v93, v99
	v_add_f32_e32 v99, v94, v99
	v_add_f32_e32 v99, v95, v99
	v_cvt_pk_bf16_f32 v164, v90, v91
	v_cvt_pk_bf16_f32 v165, v92, v93
	ds_read_b64_tr_b16 v[90:91], v0 offset:36864
	ds_read_b64_tr_b16 v[92:93], v0 offset:37376
	v_mfma_f32_32x32x16_bf16 v[100:115], v[188:191], v[152:155], v[100:115]
	v_add_f32_e32 v99, v96, v99
	v_add_f32_e32 v99, v97, v99
	v_add_f32_e32 v99, v66, v99
	v_add_f32_e32 v99, v67, v99
	v_cvt_pk_bf16_f32 v166, v94, v95
	v_cvt_pk_bf16_f32 v167, v96, v97
	ds_read_b64_tr_b16 v[94:95], v0 offset:25600
	ds_read_b64_tr_b16 v[96:97], v0 offset:26112
	v_mfma_f32_32x32x16_bf16 v[116:131], v[184:187], v[148:151], v[116:131]
	v_add_f32_e32 v99, v68, v99
	v_add_f32_e32 v99, v69, v99
	v_add_f32_e32 v99, v70, v99
	v_add_f32_e32 v99, v71, v99
	v_cvt_pk_bf16_f32 v156, v66, v67
	v_cvt_pk_bf16_f32 v157, v68, v69
	ds_read_b64_tr_b16 v[66:67], v0 offset:29696
	ds_read_b64_tr_b16 v[68:69], v0 offset:30208
	v_mfma_f32_32x32x16_bf16 v[100:115], v[180:183], v[148:151], v[100:115]
	v_add_f32_e32 v99, v72, v99
	v_add_f32_e32 v99, v73, v99
	v_add_f32_e32 v99, v74, v99
	v_add_f32_e32 v99, v75, v99
	v_cvt_pk_bf16_f32 v158, v70, v71
	v_cvt_pk_bf16_f32 v159, v72, v73
	ds_read_b64_tr_b16 v[70:71], v0 offset:33792
	ds_read_b64_tr_b16 v[72:73], v0 offset:34304
	v_mfma_f32_32x32x16_bf16 v[116:131], v[176:179], v[132:135], v[116:131]
	v_add_f32_e32 v99, v76, v99
	v_add_f32_e32 v99, v77, v99
	v_add_f32_e32 v99, v78, v99
	v_add_f32_e32 v99, v79, v99
	v_cvt_pk_bf16_f32 v144, v74, v75
	v_cvt_pk_bf16_f32 v145, v76, v77
	ds_read_b64_tr_b16 v[74:75], v0 offset:37888
	ds_read_b64_tr_b16 v[76:77], v0 offset:38400
	v_mfma_f32_32x32x16_bf16 v[100:115], v[172:175], v[132:135], v[100:115]
	v_add_f32_e32 v99, v80, v99
	v_add_f32_e32 v99, v81, v99
	v_add_f32_e32 v99, 0, v99
	v_cvt_pk_bf16_f32 v146, v78, v79
	v_cvt_pk_bf16_f32 v147, v80, v81
	v_lshl_add_u64 v[208:209], v[216:217], 0, s[54:55]
	v_lshl_add_u64 v[78:79], v[208:209], 0, s[46:47]
	s_add_i32 s56, s62, s91
	v_lshl_add_u64 v[210:211], v[218:219], 0, s[54:55]
	s_mov_b32 m0, s56
	s_nop 0
	global_load_lds_dwordx4 v[78:79], off
	v_lshl_add_u64 v[78:79], v[210:211], 0, s[40:41]
	s_lshl_b32 s56, s61, 1
	v_lshl_add_u64 v[222:223], v[220:221], 0, s[54:55]
	s_add_i32 s57, s56, s92
	s_mov_b32 m0, s57
	s_nop 0
	global_load_lds_dwordx4 v[78:79], off
	v_lshl_add_u64 v[78:79], v[222:223], 0, s[40:41]
	s_add_i32 s56, s56, s93
	s_mov_b32 m0, s56
	s_nop 0
	global_load_lds_dwordx4 v[78:79], off
	s_waitcnt lgkmcnt(14)
	v_mfma_f32_32x32x16_bf16 v[50:65], v[168:171], v[204:207], v[50:65]
	ds_read_b64_tr_b16 v[78:79], v0 offset:26624
	ds_read_b64_tr_b16 v[80:81], v0 offset:27136
	v_max_f32_e32 v253, v117, v117
	v_max_f32_e32 v254, v116, v116
	v_max_f32_e32 v253, v254, v253
	v_max3_f32 v254, v118, v119, v101
	v_max3_f32 v253, v253, v100, v102
	s_waitcnt lgkmcnt(14)
	v_mfma_f32_32x32x16_bf16 v[34:49], v[168:171], v[82:85], v[34:49]
	ds_read_b64_tr_b16 v[82:83], v0 offset:30720
	ds_read_b64_tr_b16 v[84:85], v0 offset:31232
	v_max3_f32 v253, v253, v103, v120
	v_max3_f32 v254, v254, v122, v123
	v_max3_f32 v253, v253, v121, v104
	v_max3_f32 v254, v254, v106, v107
	v_max3_f32 v253, v253, v105, v124
	s_waitcnt lgkmcnt(14)
	v_mfma_f32_32x32x16_bf16 v[18:33], v[168:171], v[86:89], v[18:33]
	ds_read_b64_tr_b16 v[86:87], v0 offset:34816
	ds_read_b64_tr_b16 v[88:89], v0 offset:35328
	v_max3_f32 v254, v254, v126, v127
	v_max3_f32 v253, v253, v125, v108
	v_max3_f32 v254, v254, v110, v111
	v_max3_f32 v253, v253, v109, v128
	v_max3_f32 v254, v254, v130, v131
	s_waitcnt lgkmcnt(14)
	v_mfma_f32_32x32x16_bf16 v[2:17], v[168:171], v[90:93], v[2:17]
	ds_read_b64_tr_b16 v[90:91], v0 offset:38912
	ds_read_b64_tr_b16 v[92:93], v0 offset:39424
	v_max3_f32 v253, v253, v129, v112
	v_max3_f32 v254, v254, v114, v115
	v_max3_f32 v253, v253, v113, v254
	v_mov_b32_e32 v254, v253
	s_nop 1
	v_permlane32_swap_b32_e32 v253, v254
	v_max_f32_e32 v254, v254, v254
	v_max_f32_e32 v253, v253, v253
	v_max_f32_e32 v253, v253, v254
	v_cmp_lt_f32_e32 vcc, s87, v253
	s_cmp_lg_u64 vcc, 0
	v_add_f32_e32 v98, v98, v99
	s_cselect_b64 s[56:57], -1, 0
	s_cbranch_vccnz .LBB0_1360

.LBB0_1355:
	s_add_i32 s56, s61, 0x2000
	s_cmpk_lg_i32 s61, 0x4000
	s_cselect_b32 s95, s56, 0
	s_lshl_b32 s56, s62, 1
	s_add_i32 s63, s63, -4
	v_add_u32_e32 v99, s56, v242
	v_cvt_f32_i32_e32 v70, s63
	ds_read_b64_tr_b16 v[200:201], v99 offset:24576
	ds_read_b64_tr_b16 v[202:203], v99 offset:25088
	v_lshrrev_b32_e32 v70, 16, v70
	v_cndmask_b32_e64 v70, 0, v70, s[10:11]
	v_mov_b32_e32 v71, v240
	v_lshlrev_b32_e32 v72, 16, v70
	v_or_b32_e32 v142, v72, v70
	v_lshl_or_b32 v140, v71, 16, v71
	v_or_b32_e32 v141, v71, v72
	v_add_f32_e32 v70, v116, v117
	v_cvt_pk_bf16_f32 v168, v116, v117
	v_mfma_f32_32x32x16_bf16 v[82:97], v[140:143], v[136:139], 0
	v_cvt_pk_bf16_f32 v169, v118, v119
	v_mfma_f32_32x32x16_bf16 v[82:97], v[66:69], v[160:163], v[82:97]
	v_add_f32_e32 v66, v118, v70
	v_add_f32_e32 v66, v119, v66
	v_add_f32_e32 v66, v120, v66
	v_add_f32_e32 v144, v121, v66
	ds_read_b64_tr_b16 v[116:117], v99 offset:28672
	ds_read_b64_tr_b16 v[118:119], v99 offset:29184
	v_mov_b32_e32 v66, v239
	v_cvt_pk_bf16_f32 v170, v120, v121
	v_lshl_or_b32 v140, v66, 16, v66
	v_or_b32_e32 v141, v66, v72
	v_cvt_pk_bf16_f32 v171, v122, v123
	s_nop 0
	v_mfma_f32_32x32x16_bf16 v[66:81], v[140:143], v[136:139], 0
	v_add_f32_e32 v140, v122, v144
	v_add_f32_e32 v140, v123, v140
	v_add_f32_e32 v140, v124, v140
	v_add_f32_e32 v140, v125, v140
	v_mfma_f32_32x32x16_bf16 v[66:81], v[196:199], v[160:163], v[66:81]
	ds_read_b64_tr_b16 v[120:121], v99 offset:32768
	ds_read_b64_tr_b16 v[122:123], v99 offset:33280
	v_mfma_f32_32x32x16_bf16 v[82:97], v[192:195], v[152:155], v[82:97]
	v_add_f32_e32 v140, v126, v140
	v_add_f32_e32 v140, v127, v140
	v_add_f32_e32 v140, v128, v140
	v_add_f32_e32 v140, v129, v140
	v_cvt_pk_bf16_f32 v164, v124, v125
	v_cvt_pk_bf16_f32 v165, v126, v127
	ds_read_b64_tr_b16 v[124:125], v99 offset:36864
	ds_read_b64_tr_b16 v[126:127], v99 offset:37376
	v_mfma_f32_32x32x16_bf16 v[66:81], v[188:191], v[152:155], v[66:81]
	v_add_f32_e32 v140, v130, v140
	v_add_f32_e32 v140, v131, v140
	v_add_f32_e32 v140, v100, v140
	v_add_f32_e32 v140, v101, v140
	v_cvt_pk_bf16_f32 v166, v128, v129
	v_cvt_pk_bf16_f32 v167, v130, v131
	ds_read_b64_tr_b16 v[128:129], v99 offset:25600
	ds_read_b64_tr_b16 v[130:131], v99 offset:26112
	v_mfma_f32_32x32x16_bf16 v[82:97], v[184:187], v[148:151], v[82:97]
	v_add_f32_e32 v140, v102, v140
	v_add_f32_e32 v140, v103, v140
	v_add_f32_e32 v140, v104, v140
	v_add_f32_e32 v140, v105, v140
	v_cvt_pk_bf16_f32 v156, v100, v101
	v_cvt_pk_bf16_f32 v157, v102, v103
	ds_read_b64_tr_b16 v[100:101], v99 offset:29696
	ds_read_b64_tr_b16 v[102:103], v99 offset:30208
	v_mfma_f32_32x32x16_bf16 v[66:81], v[180:183], v[148:151], v[66:81]
	v_add_f32_e32 v140, v106, v140
	v_add_f32_e32 v140, v107, v140
	v_add_f32_e32 v140, v108, v140
	v_add_f32_e32 v140, v109, v140
	v_cvt_pk_bf16_f32 v158, v104, v105
	v_cvt_pk_bf16_f32 v159, v106, v107
	ds_read_b64_tr_b16 v[104:105], v99 offset:33792
	ds_read_b64_tr_b16 v[106:107], v99 offset:34304
	v_mfma_f32_32x32x16_bf16 v[82:97], v[176:179], v[132:135], v[82:97]
	v_add_f32_e32 v140, v110, v140
	v_add_f32_e32 v140, v111, v140
	v_add_f32_e32 v140, v112, v140
	v_add_f32_e32 v140, v113, v140
	v_cvt_pk_bf16_f32 v144, v108, v109
	v_cvt_pk_bf16_f32 v145, v110, v111
	ds_read_b64_tr_b16 v[108:109], v99 offset:37888
	ds_read_b64_tr_b16 v[110:111], v99 offset:38400
	v_mfma_f32_32x32x16_bf16 v[66:81], v[172:175], v[132:135], v[66:81]
	v_add_f32_e32 v140, v114, v140
	v_add_f32_e32 v140, v115, v140
	v_add_f32_e32 v140, 0, v140
	v_cvt_pk_bf16_f32 v146, v112, v113
	v_cvt_pk_bf16_f32 v147, v114, v115
	v_lshl_add_u64 v[112:113], v[208:209], 0, s[48:49]
	s_add_i32 s56, s61, s91
	s_mov_b32 m0, s56
	s_nop 0
	global_load_lds_dwordx4 v[112:113], off
	v_lshl_add_u64 v[112:113], v[210:211], 0, s[42:43]
	s_lshl_b32 s56, s95, 1
	s_add_i32 s57, s56, s92
	s_mov_b32 m0, s57
	s_nop 0
	global_load_lds_dwordx4 v[112:113], off
	v_lshl_add_u64 v[112:113], v[222:223], 0, s[42:43]
	s_add_i32 s56, s56, s93
	s_mov_b32 m0, s56
	s_nop 0
	global_load_lds_dwordx4 v[112:113], off
	s_waitcnt lgkmcnt(14)
	v_mfma_f32_32x32x16_bf16 v[50:65], v[168:171], v[200:203], v[50:65]
	ds_read_b64_tr_b16 v[112:113], v99 offset:26624
	ds_read_b64_tr_b16 v[114:115], v99 offset:27136
	v_max_f32_e32 v253, v83, v83
	v_max_f32_e32 v254, v82, v82
	v_max_f32_e32 v253, v254, v253
	v_max3_f32 v254, v84, v85, v67
	v_max3_f32 v253, v253, v66, v68
	s_waitcnt lgkmcnt(14)
	v_mfma_f32_32x32x16_bf16 v[34:49], v[168:171], v[116:119], v[34:49]
	ds_read_b64_tr_b16 v[116:117], v99 offset:30720
	ds_read_b64_tr_b16 v[118:119], v99 offset:31232
	v_max3_f32 v253, v253, v69, v86
	v_max3_f32 v254, v254, v88, v89
	v_max3_f32 v253, v253, v87, v70
	v_max3_f32 v254, v254, v72, v73
	v_max3_f32 v253, v253, v71, v90
	s_waitcnt lgkmcnt(14)
	v_mfma_f32_32x32x16_bf16 v[18:33], v[168:171], v[120:123], v[18:33]
	ds_read_b64_tr_b16 v[120:121], v99 offset:34816
	ds_read_b64_tr_b16 v[122:123], v99 offset:35328
	v_max3_f32 v254, v254, v92, v93
	v_max3_f32 v253, v253, v91, v74
	v_max3_f32 v254, v254, v76, v77
	v_max3_f32 v253, v253, v75, v94
	v_max3_f32 v254, v254, v96, v97
	s_waitcnt lgkmcnt(14)
	v_mfma_f32_32x32x16_bf16 v[2:17], v[168:171], v[124:127], v[2:17]
	ds_read_b64_tr_b16 v[124:125], v99 offset:38912
	ds_read_b64_tr_b16 v[126:127], v99 offset:39424
	v_max3_f32 v253, v253, v95, v78
	v_max3_f32 v254, v254, v80, v81
	v_max3_f32 v253, v253, v79, v254
	v_mov_b32_e32 v254, v253
	s_nop 1
	v_permlane32_swap_b32_e32 v253, v254
	v_max_f32_e32 v254, v254, v254
	v_max_f32_e32 v253, v253, v253
	v_max_f32_e32 v253, v253, v254
	v_cmp_lt_f32_e32 vcc, s87, v253
	s_cmp_lg_u64 vcc, 0
	v_add_f32_e32 v98, v98, v140
	s_cselect_b64 s[56:57], -1, 0
	s_cbranch_vccnz .LBB0_1363
